# E37: RMW-type phases: peeled first iteration no longer waits for the previous epilogue's stores/atomics (L1' vmcnt(8)->vmcnt(32); L2' counted wait only in the phase's first unit); on E28
# speedup vs baseline: 1.0006x; 1.0006x over previous
.LBB0_579:
	s_mul_i32 s73, s72, 0x2c0000
	s_and_b64 s[8:9], s[42:43], exec
	s_mul_i32 s84, s71, 0x2c0000
	s_cselect_b32 s8, s73, s21
	s_cselect_b32 s9, s84, s13
	s_addk_i32 s13, 0x100
	s_add_i32 s21, s21, 0xc000
	s_mov_b32 s22, -2
	s_waitcnt lgkmcnt(0)
	v_add_u32_e32 v154, 0x10000, v140
	ds_read_b128 v[132:135], v154
	ds_read_b128 v[142:145], v154 offset:1024
	ds_read_b128 v[170:173], v154 offset:2048
	ds_read_b128 v[174:177], v154 offset:3072
	v_add_u32_e32 v154, 0x14000, v140
	ds_read_b128 v[178:181], v154
	ds_read_b128 v[182:185], v154 offset:1024
	ds_read_b128 v[186:189], v154 offset:2048
	ds_read_b128 v[190:193], v154 offset:3072
	s_add_i32 s23, s21, 0x4000
	s_cmpk_eq_i32 s22, 0x54
	s_cselect_b32 s27, s8, s23
	s_cselect_b32 s26, s9, s13
	s_or_b32 s23, s27, 0x8000
	s_mov_b32 m0, s68
	ds_read_b128 v[194:197], v141
	ds_read_b128 v[198:201], v141 offset:1024
	ds_read_b128 v[202:205], v141 offset:2048
	ds_read_b128 v[228:231], v141 offset:3072
	ds_read_b128 v[232:235], v141 offset:4096
	ds_read_b128 v[236:239], v141 offset:5120
	ds_read_b128 v[240:243], v141 offset:6144
	ds_read_b128 v[244:247], v141 offset:7168
	buffer_load_dwordx4 v136, s[60:63], s21 offen lds
	s_mov_b32 m0, s70
	s_nop 0
	buffer_load_dwordx4 v138, s[60:63], s21 offen lds
	s_waitcnt vmcnt(32)
	s_waitcnt lgkmcnt(0)
	s_setprio 1
	s_barrier
	v_mfma_f32_16x16x32_bf16 v[126:129], v[132:135], v[194:197], 0
	v_mfma_f32_16x16x32_bf16 v[126:129], v[142:145], v[198:201], v[126:129]
	v_mfma_f32_16x16x32_bf16 v[106:109], v[170:173], v[194:197], 0
	v_mfma_f32_16x16x32_bf16 v[106:109], v[174:177], v[198:201], v[106:109]
	v_mfma_f32_16x16x32_bf16 v[110:113], v[186:189], v[194:197], 0
	v_mfma_f32_16x16x32_bf16 v[110:113], v[190:193], v[198:201], v[110:113]
	v_mfma_f32_16x16x32_bf16 v[122:125], v[178:181], v[194:197], 0
	v_mfma_f32_16x16x32_bf16 v[122:125], v[182:185], v[198:201], v[122:125]
	v_mfma_f32_16x16x32_bf16 v[102:105], v[178:181], v[202:205], 0
	v_mfma_f32_16x16x32_bf16 v[102:105], v[182:185], v[228:231], v[102:105]
	v_mfma_f32_16x16x32_bf16 v[98:101], v[186:189], v[202:205], 0
	v_mfma_f32_16x16x32_bf16 v[98:101], v[190:193], v[228:231], v[98:101]
	v_mfma_f32_16x16x32_bf16 v[114:117], v[170:173], v[202:205], 0
	v_mfma_f32_16x16x32_bf16 v[114:117], v[174:177], v[228:231], v[114:117]
	v_mfma_f32_16x16x32_bf16 v[118:121], v[132:135], v[202:205], 0
	v_mfma_f32_16x16x32_bf16 v[118:121], v[142:145], v[228:231], v[118:121]
	v_mfma_f32_16x16x32_bf16 v[94:97], v[132:135], v[232:235], 0
	v_mfma_f32_16x16x32_bf16 v[94:97], v[142:145], v[236:239], v[94:97]
	v_mfma_f32_16x16x32_bf16 v[90:93], v[170:173], v[232:235], 0
	v_mfma_f32_16x16x32_bf16 v[90:93], v[174:177], v[236:239], v[90:93]
	v_mfma_f32_16x16x32_bf16 v[82:85], v[186:189], v[232:235], 0
	v_mfma_f32_16x16x32_bf16 v[82:85], v[190:193], v[236:239], v[82:85]
	v_mfma_f32_16x16x32_bf16 v[86:89], v[178:181], v[232:235], 0
	v_mfma_f32_16x16x32_bf16 v[86:89], v[182:185], v[236:239], v[86:89]
	v_mfma_f32_16x16x32_bf16 v[70:73], v[178:181], v[240:243], 0
	v_mfma_f32_16x16x32_bf16 v[70:73], v[182:185], v[244:247], v[70:73]
	v_mfma_f32_16x16x32_bf16 v[66:69], v[186:189], v[240:243], 0
	v_mfma_f32_16x16x32_bf16 v[66:69], v[190:193], v[244:247], v[66:69]
	v_mfma_f32_16x16x32_bf16 v[74:77], v[170:173], v[240:243], 0
	v_mfma_f32_16x16x32_bf16 v[74:77], v[174:177], v[244:247], v[74:77]
	v_mfma_f32_16x16x32_bf16 v[78:81], v[132:135], v[240:243], 0
	v_mfma_f32_16x16x32_bf16 v[78:81], v[142:145], v[244:247], v[78:81]
	s_barrier
	s_setprio 0
	s_mov_b32 s46, s62
	s_mov_b32 s47, s63
	s_mov_b32 m0, s15
	ds_read_b128 v[194:197], v141 offset:16384
	buffer_load_dwordx4 v137, s[44:47], s26 offen lds
	s_add_i32 s52, s26, 0x160000
	s_mov_b32 m0, s16
	ds_read_b128 v[198:201], v141 offset:17408
	buffer_load_dwordx4 v139, s[44:47], s26 offen lds
	s_mov_b32 m0, s18
	ds_read_b128 v[202:205], v141 offset:18432
	buffer_load_dwordx4 v137, s[44:47], s52 offen lds
	s_mov_b32 m0, s19
	ds_read_b128 v[228:231], v141 offset:19456
	buffer_load_dwordx4 v139, s[44:47], s52 offen lds
	s_mov_b32 m0, s14
	ds_read_b128 v[232:235], v141 offset:20480
	buffer_load_dwordx4 v136, s[60:63], s27 offen lds
	s_mov_b32 m0, s24
	ds_read_b128 v[236:239], v141 offset:21504
	buffer_load_dwordx4 v138, s[60:63], s27 offen lds
	ds_read_b128 v[240:243], v141 offset:22528
	ds_read_b128 v[244:247], v141 offset:23552
	s_cmp_lg_u32 s69, 1
	s_cbranch_scc1 .Lgk_w2_0
	s_waitcnt vmcnt(8)
.Lgk_w2_0:
	s_waitcnt lgkmcnt(0)
	s_setprio 1
	s_barrier
	v_mfma_f32_16x16x32_bf16 v[62:65], v[132:135], v[194:197], 0
	v_mfma_f32_16x16x32_bf16 v[62:65], v[142:145], v[198:201], v[62:65]
	v_mfma_f32_16x16x32_bf16 v[58:61], v[170:173], v[194:197], 0
	v_mfma_f32_16x16x32_bf16 v[58:61], v[174:177], v[198:201], v[58:61]
	v_mfma_f32_16x16x32_bf16 v[50:53], v[186:189], v[194:197], 0
	v_mfma_f32_16x16x32_bf16 v[50:53], v[190:193], v[198:201], v[50:53]
	v_mfma_f32_16x16x32_bf16 v[54:57], v[178:181], v[194:197], 0
	v_mfma_f32_16x16x32_bf16 v[54:57], v[182:185], v[198:201], v[54:57]
	v_mfma_f32_16x16x32_bf16 v[38:41], v[178:181], v[202:205], 0
	v_mfma_f32_16x16x32_bf16 v[38:41], v[182:185], v[228:231], v[38:41]
	v_mfma_f32_16x16x32_bf16 v[34:37], v[186:189], v[202:205], 0
	v_mfma_f32_16x16x32_bf16 v[34:37], v[190:193], v[228:231], v[34:37]
	v_mfma_f32_16x16x32_bf16 v[42:45], v[170:173], v[202:205], 0
	v_mfma_f32_16x16x32_bf16 v[42:45], v[174:177], v[228:231], v[42:45]
	v_mfma_f32_16x16x32_bf16 v[46:49], v[132:135], v[202:205], 0
	v_mfma_f32_16x16x32_bf16 v[46:49], v[142:145], v[228:231], v[46:49]
	v_mfma_f32_16x16x32_bf16 v[30:33], v[132:135], v[232:235], 0
	v_mfma_f32_16x16x32_bf16 v[30:33], v[142:145], v[236:239], v[30:33]
	v_mfma_f32_16x16x32_bf16 v[26:29], v[170:173], v[232:235], 0
	v_mfma_f32_16x16x32_bf16 v[26:29], v[174:177], v[236:239], v[26:29]
	v_mfma_f32_16x16x32_bf16 v[18:21], v[186:189], v[232:235], 0
	v_mfma_f32_16x16x32_bf16 v[18:21], v[190:193], v[236:239], v[18:21]
	v_mfma_f32_16x16x32_bf16 v[22:25], v[178:181], v[232:235], 0
	v_mfma_f32_16x16x32_bf16 v[22:25], v[182:185], v[236:239], v[22:25]
	v_mfma_f32_16x16x32_bf16 v[6:9], v[178:181], v[240:243], 0
	v_mfma_f32_16x16x32_bf16 v[6:9], v[182:185], v[244:247], v[6:9]
	v_mfma_f32_16x16x32_bf16 v[2:5], v[186:189], v[240:243], 0
	v_mfma_f32_16x16x32_bf16 v[2:5], v[190:193], v[244:247], v[2:5]
	v_mfma_f32_16x16x32_bf16 v[10:13], v[170:173], v[240:243], 0
	v_mfma_f32_16x16x32_bf16 v[10:13], v[174:177], v[244:247], v[10:13]
	v_mfma_f32_16x16x32_bf16 v[14:17], v[132:135], v[240:243], 0
	v_mfma_f32_16x16x32_bf16 v[14:17], v[142:145], v[244:247], v[14:17]
	s_barrier
	s_setprio 0
	v_add_u32_e32 v154, 0x18000, v140
	ds_read_b128 v[132:135], v154
	ds_read_b128 v[142:145], v154 offset:1024
	ds_read_b128 v[170:173], v154 offset:2048
	ds_read_b128 v[174:177], v154 offset:3072
	v_add_u32_e32 v154, 0x1c000, v140
	ds_read_b128 v[178:181], v154
	ds_read_b128 v[182:185], v154 offset:1024
	ds_read_b128 v[186:189], v154 offset:2048
	ds_read_b128 v[190:193], v154 offset:3072
	s_bitset1_b32 s27, 14
	s_mov_b32 m0, s25
	ds_read_b128 v[194:197], v141 offset:32768
	ds_read_b128 v[198:201], v141 offset:33792
	ds_read_b128 v[202:205], v141 offset:34816
	ds_read_b128 v[228:231], v141 offset:35840
	ds_read_b128 v[232:235], v141 offset:36864
	ds_read_b128 v[236:239], v141 offset:37888
	ds_read_b128 v[240:243], v141 offset:38912
	ds_read_b128 v[244:247], v141 offset:39936
	buffer_load_dwordx4 v136, s[60:63], s27 offen lds
	s_mov_b32 m0, s30
	s_nop 0
	buffer_load_dwordx4 v138, s[60:63], s27 offen lds
	s_waitcnt vmcnt(8)
	s_waitcnt lgkmcnt(0)
	s_setprio 1
	s_barrier
	v_mfma_f32_16x16x32_bf16 v[126:129], v[132:135], v[194:197], v[126:129]
	v_mfma_f32_16x16x32_bf16 v[126:129], v[142:145], v[198:201], v[126:129]
	v_mfma_f32_16x16x32_bf16 v[106:109], v[170:173], v[194:197], v[106:109]
	v_mfma_f32_16x16x32_bf16 v[106:109], v[174:177], v[198:201], v[106:109]
	v_mfma_f32_16x16x32_bf16 v[110:113], v[186:189], v[194:197], v[110:113]
	v_mfma_f32_16x16x32_bf16 v[110:113], v[190:193], v[198:201], v[110:113]
	v_mfma_f32_16x16x32_bf16 v[122:125], v[178:181], v[194:197], v[122:125]
	v_mfma_f32_16x16x32_bf16 v[122:125], v[182:185], v[198:201], v[122:125]
	v_mfma_f32_16x16x32_bf16 v[102:105], v[178:181], v[202:205], v[102:105]
	v_mfma_f32_16x16x32_bf16 v[102:105], v[182:185], v[228:231], v[102:105]
	v_mfma_f32_16x16x32_bf16 v[98:101], v[186:189], v[202:205], v[98:101]
	v_mfma_f32_16x16x32_bf16 v[98:101], v[190:193], v[228:231], v[98:101]
	v_mfma_f32_16x16x32_bf16 v[114:117], v[170:173], v[202:205], v[114:117]
	v_mfma_f32_16x16x32_bf16 v[114:117], v[174:177], v[228:231], v[114:117]
	v_mfma_f32_16x16x32_bf16 v[118:121], v[132:135], v[202:205], v[118:121]
	v_mfma_f32_16x16x32_bf16 v[118:121], v[142:145], v[228:231], v[118:121]
	v_mfma_f32_16x16x32_bf16 v[94:97], v[132:135], v[232:235], v[94:97]
	v_mfma_f32_16x16x32_bf16 v[94:97], v[142:145], v[236:239], v[94:97]
	v_mfma_f32_16x16x32_bf16 v[90:93], v[170:173], v[232:235], v[90:93]
	v_mfma_f32_16x16x32_bf16 v[90:93], v[174:177], v[236:239], v[90:93]
	v_mfma_f32_16x16x32_bf16 v[82:85], v[186:189], v[232:235], v[82:85]
	v_mfma_f32_16x16x32_bf16 v[82:85], v[190:193], v[236:239], v[82:85]
	v_mfma_f32_16x16x32_bf16 v[86:89], v[178:181], v[232:235], v[86:89]
	v_mfma_f32_16x16x32_bf16 v[86:89], v[182:185], v[236:239], v[86:89]
	v_mfma_f32_16x16x32_bf16 v[70:73], v[178:181], v[240:243], v[70:73]
	v_mfma_f32_16x16x32_bf16 v[70:73], v[182:185], v[244:247], v[70:73]
	v_mfma_f32_16x16x32_bf16 v[66:69], v[186:189], v[240:243], v[66:69]
	v_mfma_f32_16x16x32_bf16 v[66:69], v[190:193], v[244:247], v[66:69]
	v_mfma_f32_16x16x32_bf16 v[74:77], v[170:173], v[240:243], v[74:77]
	v_mfma_f32_16x16x32_bf16 v[74:77], v[174:177], v[244:247], v[74:77]
	v_mfma_f32_16x16x32_bf16 v[78:81], v[132:135], v[240:243], v[78:81]
	v_mfma_f32_16x16x32_bf16 v[78:81], v[142:145], v[244:247], v[78:81]
	s_barrier
	s_setprio 0
	s_or_b32 s27, s26, 0x80
	s_mov_b32 m0, s36
	ds_read_b128 v[194:197], v141 offset:49152
	buffer_load_dwordx4 v137, s[44:47], s27 offen lds
	s_add_i32 s26, s26, 0x160080
	s_mov_b32 m0, s37
	ds_read_b128 v[198:201], v141 offset:50176
	buffer_load_dwordx4 v139, s[44:47], s27 offen lds
	s_mov_b32 m0, s66
	ds_read_b128 v[202:205], v141 offset:51200
	buffer_load_dwordx4 v137, s[44:47], s26 offen lds
	s_mov_b32 m0, s67
	ds_read_b128 v[228:231], v141 offset:52224
	buffer_load_dwordx4 v139, s[44:47], s26 offen lds
	s_mov_b32 m0, s48
	ds_read_b128 v[232:235], v141 offset:53248
	buffer_load_dwordx4 v136, s[60:63], s23 offen lds
	s_mov_b32 m0, s49
	ds_read_b128 v[236:239], v141 offset:54272
	buffer_load_dwordx4 v138, s[60:63], s23 offen lds
	ds_read_b128 v[240:243], v141 offset:55296
	ds_read_b128 v[244:247], v141 offset:56320
	s_waitcnt vmcnt(8)
	s_waitcnt lgkmcnt(0)
	s_setprio 1
	s_barrier
	v_mfma_f32_16x16x32_bf16 v[62:65], v[132:135], v[194:197], v[62:65]
	v_mfma_f32_16x16x32_bf16 v[62:65], v[142:145], v[198:201], v[62:65]
	v_mfma_f32_16x16x32_bf16 v[58:61], v[170:173], v[194:197], v[58:61]
	v_mfma_f32_16x16x32_bf16 v[58:61], v[174:177], v[198:201], v[58:61]
	v_mfma_f32_16x16x32_bf16 v[50:53], v[186:189], v[194:197], v[50:53]
	v_mfma_f32_16x16x32_bf16 v[50:53], v[190:193], v[198:201], v[50:53]
	v_mfma_f32_16x16x32_bf16 v[54:57], v[178:181], v[194:197], v[54:57]
	v_mfma_f32_16x16x32_bf16 v[54:57], v[182:185], v[198:201], v[54:57]
	v_mfma_f32_16x16x32_bf16 v[38:41], v[178:181], v[202:205], v[38:41]
	v_mfma_f32_16x16x32_bf16 v[38:41], v[182:185], v[228:231], v[38:41]
	v_mfma_f32_16x16x32_bf16 v[34:37], v[186:189], v[202:205], v[34:37]
	v_mfma_f32_16x16x32_bf16 v[34:37], v[190:193], v[228:231], v[34:37]
	v_mfma_f32_16x16x32_bf16 v[42:45], v[170:173], v[202:205], v[42:45]
	v_mfma_f32_16x16x32_bf16 v[42:45], v[174:177], v[228:231], v[42:45]
	v_mfma_f32_16x16x32_bf16 v[46:49], v[132:135], v[202:205], v[46:49]
	v_mfma_f32_16x16x32_bf16 v[46:49], v[142:145], v[228:231], v[46:49]
	v_mfma_f32_16x16x32_bf16 v[30:33], v[132:135], v[232:235], v[30:33]
	v_mfma_f32_16x16x32_bf16 v[30:33], v[142:145], v[236:239], v[30:33]
	v_mfma_f32_16x16x32_bf16 v[26:29], v[170:173], v[232:235], v[26:29]
	v_mfma_f32_16x16x32_bf16 v[26:29], v[174:177], v[236:239], v[26:29]
	v_mfma_f32_16x16x32_bf16 v[18:21], v[186:189], v[232:235], v[18:21]
	v_mfma_f32_16x16x32_bf16 v[18:21], v[190:193], v[236:239], v[18:21]
	v_mfma_f32_16x16x32_bf16 v[22:25], v[178:181], v[232:235], v[22:25]
	v_mfma_f32_16x16x32_bf16 v[22:25], v[182:185], v[236:239], v[22:25]
	v_mfma_f32_16x16x32_bf16 v[6:9], v[178:181], v[240:243], v[6:9]
	v_mfma_f32_16x16x32_bf16 v[6:9], v[182:185], v[244:247], v[6:9]
	v_mfma_f32_16x16x32_bf16 v[2:5], v[186:189], v[240:243], v[2:5]
	v_mfma_f32_16x16x32_bf16 v[2:5], v[190:193], v[244:247], v[2:5]
	v_mfma_f32_16x16x32_bf16 v[10:13], v[170:173], v[240:243], v[10:13]
	v_mfma_f32_16x16x32_bf16 v[10:13], v[174:177], v[244:247], v[10:13]
	v_mfma_f32_16x16x32_bf16 v[14:17], v[132:135], v[240:243], v[14:17]
	v_mfma_f32_16x16x32_bf16 v[14:17], v[142:145], v[244:247], v[14:17]
	s_barrier
	s_setprio 0
	s_addk_i32 s13, 0x100
	s_add_i32 s22, s22, 2
	s_add_i32 s21, s21, 0x10000
	s_cmpk_gt_u32 s22, 0x55

.LBB0_1588:
	s_lshl_b32 s85, s84, 20
	s_and_b64 s[8:9], s[42:43], exec
	s_cselect_b32 s8, s85, s13
	s_lshl_b32 s48, s73, 20
	s_and_b64 s[22:23], s[42:43], exec
	s_cselect_b32 s9, s48, s21
	s_add_i32 s13, s13, 0x80080
	s_addk_i32 s21, 0x100
	s_mov_b32 s22, -2
	s_waitcnt lgkmcnt(0)
	v_add_u32_e32 v170, 0x10000, v140
	v_add_u32_e32 v186, 0x14000, v140
	ds_read_b128 v[132:135], v170
	ds_read_b128 v[142:145], v170 offset:1024
	ds_read_b128 v[154:157], v170 offset:2048
	ds_read_b128 v[170:173], v170 offset:3072
	ds_read_b128 v[174:177], v186
	ds_read_b128 v[178:181], v186 offset:1024
	ds_read_b128 v[182:185], v186 offset:2048
	ds_read_b128 v[186:189], v186 offset:3072
	s_add_i32 s23, s13, 0xfff80080
	s_cmp_eq_u32 s22, 28
	s_cselect_b32 s27, s8, s23
	s_cselect_b32 s26, s9, s21
	s_or_b32 s23, s27, 0x80
	s_mov_b32 m0, s70
	ds_read_b128 v[190:193], v141
	ds_read_b128 v[194:197], v141 offset:1024
	ds_read_b128 v[198:201], v141 offset:2048
	ds_read_b128 v[202:205], v141 offset:3072
	ds_read_b128 v[228:231], v141 offset:4096
	ds_read_b128 v[232:235], v141 offset:5120
	ds_read_b128 v[236:239], v141 offset:6144
	ds_read_b128 v[240:243], v141 offset:7168
	buffer_load_dwordx4 v136, s[60:63], s13 offen lds
	s_mov_b32 m0, s72
	s_nop 0
	buffer_load_dwordx4 v138, s[60:63], s13 offen lds
	s_waitcnt vmcnt(32)
	s_waitcnt lgkmcnt(0)
	s_setprio 1
	s_barrier
	v_mfma_f32_16x16x32_bf16 v[126:129], v[132:135], v[190:193], 0
	v_mfma_f32_16x16x32_bf16 v[126:129], v[142:145], v[194:197], v[126:129]
	v_mfma_f32_16x16x32_bf16 v[106:109], v[154:157], v[190:193], 0
	v_mfma_f32_16x16x32_bf16 v[106:109], v[170:173], v[194:197], v[106:109]
	v_mfma_f32_16x16x32_bf16 v[110:113], v[182:185], v[190:193], 0
	v_mfma_f32_16x16x32_bf16 v[110:113], v[186:189], v[194:197], v[110:113]
	v_mfma_f32_16x16x32_bf16 v[122:125], v[174:177], v[190:193], 0
	v_mfma_f32_16x16x32_bf16 v[122:125], v[178:181], v[194:197], v[122:125]
	v_mfma_f32_16x16x32_bf16 v[102:105], v[174:177], v[198:201], 0
	v_mfma_f32_16x16x32_bf16 v[102:105], v[178:181], v[202:205], v[102:105]
	v_mfma_f32_16x16x32_bf16 v[98:101], v[182:185], v[198:201], 0
	v_mfma_f32_16x16x32_bf16 v[98:101], v[186:189], v[202:205], v[98:101]
	v_mfma_f32_16x16x32_bf16 v[114:117], v[154:157], v[198:201], 0
	v_mfma_f32_16x16x32_bf16 v[114:117], v[170:173], v[202:205], v[114:117]
	v_mfma_f32_16x16x32_bf16 v[118:121], v[132:135], v[198:201], 0
	v_mfma_f32_16x16x32_bf16 v[118:121], v[142:145], v[202:205], v[118:121]
	v_mfma_f32_16x16x32_bf16 v[94:97], v[132:135], v[228:231], 0
	v_mfma_f32_16x16x32_bf16 v[94:97], v[142:145], v[232:235], v[94:97]
	v_mfma_f32_16x16x32_bf16 v[90:93], v[154:157], v[228:231], 0
	v_mfma_f32_16x16x32_bf16 v[90:93], v[170:173], v[232:235], v[90:93]
	v_mfma_f32_16x16x32_bf16 v[82:85], v[182:185], v[228:231], 0
	v_mfma_f32_16x16x32_bf16 v[82:85], v[186:189], v[232:235], v[82:85]
	v_mfma_f32_16x16x32_bf16 v[86:89], v[174:177], v[228:231], 0
	v_mfma_f32_16x16x32_bf16 v[86:89], v[178:181], v[232:235], v[86:89]
	v_mfma_f32_16x16x32_bf16 v[70:73], v[174:177], v[236:239], 0
	v_mfma_f32_16x16x32_bf16 v[70:73], v[178:181], v[240:243], v[70:73]
	v_mfma_f32_16x16x32_bf16 v[66:69], v[182:185], v[236:239], 0
	v_mfma_f32_16x16x32_bf16 v[66:69], v[186:189], v[240:243], v[66:69]
	v_mfma_f32_16x16x32_bf16 v[74:77], v[154:157], v[236:239], 0
	v_mfma_f32_16x16x32_bf16 v[74:77], v[170:173], v[240:243], v[74:77]
	v_mfma_f32_16x16x32_bf16 v[78:81], v[132:135], v[236:239], 0
	v_mfma_f32_16x16x32_bf16 v[78:81], v[142:145], v[240:243], v[78:81]
	s_barrier
	s_setprio 0
	s_mov_b32 s46, s62
	s_mov_b32 s47, s63
	s_mov_b32 m0, s15
	ds_read_b128 v[190:193], v141 offset:16384
	buffer_load_dwordx4 v137, s[44:47], s26 offen lds
	s_add_i32 s49, s26, 0x80000
	s_mov_b32 m0, s16
	ds_read_b128 v[194:197], v141 offset:17408
	buffer_load_dwordx4 v139, s[44:47], s26 offen lds
	s_mov_b32 m0, s18
	ds_read_b128 v[198:201], v141 offset:18432
	buffer_load_dwordx4 v137, s[44:47], s49 offen lds
	s_mov_b32 m0, s19
	ds_read_b128 v[202:205], v141 offset:19456
	buffer_load_dwordx4 v139, s[44:47], s49 offen lds
	s_mov_b32 m0, s14
	ds_read_b128 v[228:231], v141 offset:20480
	buffer_load_dwordx4 v136, s[60:63], s27 offen lds
	s_mov_b32 m0, s24
	ds_read_b128 v[232:235], v141 offset:21504
	buffer_load_dwordx4 v138, s[60:63], s27 offen lds
	ds_read_b128 v[236:239], v141 offset:22528
	ds_read_b128 v[240:243], v141 offset:23552
	s_cmp_lg_u32 s71, 1
	s_cbranch_scc1 .Lgk_w2_1
	s_waitcnt vmcnt(8)
.Lgk_w2_1:
	s_waitcnt lgkmcnt(0)
	s_setprio 1
	s_barrier
	v_mfma_f32_16x16x32_bf16 v[62:65], v[132:135], v[190:193], 0
	v_mfma_f32_16x16x32_bf16 v[62:65], v[142:145], v[194:197], v[62:65]
	v_mfma_f32_16x16x32_bf16 v[58:61], v[154:157], v[190:193], 0
	v_mfma_f32_16x16x32_bf16 v[58:61], v[170:173], v[194:197], v[58:61]
	v_mfma_f32_16x16x32_bf16 v[50:53], v[182:185], v[190:193], 0
	v_mfma_f32_16x16x32_bf16 v[50:53], v[186:189], v[194:197], v[50:53]
	v_mfma_f32_16x16x32_bf16 v[54:57], v[174:177], v[190:193], 0
	v_mfma_f32_16x16x32_bf16 v[54:57], v[178:181], v[194:197], v[54:57]
	v_mfma_f32_16x16x32_bf16 v[38:41], v[174:177], v[198:201], 0
	v_mfma_f32_16x16x32_bf16 v[38:41], v[178:181], v[202:205], v[38:41]
	v_mfma_f32_16x16x32_bf16 v[34:37], v[182:185], v[198:201], 0
	v_mfma_f32_16x16x32_bf16 v[34:37], v[186:189], v[202:205], v[34:37]
	v_mfma_f32_16x16x32_bf16 v[42:45], v[154:157], v[198:201], 0
	v_mfma_f32_16x16x32_bf16 v[42:45], v[170:173], v[202:205], v[42:45]
	v_mfma_f32_16x16x32_bf16 v[46:49], v[132:135], v[198:201], 0
	v_mfma_f32_16x16x32_bf16 v[46:49], v[142:145], v[202:205], v[46:49]
	v_mfma_f32_16x16x32_bf16 v[30:33], v[132:135], v[228:231], 0
	v_mfma_f32_16x16x32_bf16 v[30:33], v[142:145], v[232:235], v[30:33]
	v_mfma_f32_16x16x32_bf16 v[26:29], v[154:157], v[228:231], 0
	v_mfma_f32_16x16x32_bf16 v[26:29], v[170:173], v[232:235], v[26:29]
	v_mfma_f32_16x16x32_bf16 v[18:21], v[182:185], v[228:231], 0
	v_mfma_f32_16x16x32_bf16 v[18:21], v[186:189], v[232:235], v[18:21]
	v_mfma_f32_16x16x32_bf16 v[22:25], v[174:177], v[228:231], 0
	v_mfma_f32_16x16x32_bf16 v[22:25], v[178:181], v[232:235], v[22:25]
	v_mfma_f32_16x16x32_bf16 v[6:9], v[174:177], v[236:239], 0
	v_mfma_f32_16x16x32_bf16 v[6:9], v[178:181], v[240:243], v[6:9]
	v_mfma_f32_16x16x32_bf16 v[2:5], v[182:185], v[236:239], 0
	v_mfma_f32_16x16x32_bf16 v[2:5], v[186:189], v[240:243], v[2:5]
	v_mfma_f32_16x16x32_bf16 v[10:13], v[154:157], v[236:239], 0
	v_mfma_f32_16x16x32_bf16 v[10:13], v[170:173], v[240:243], v[10:13]
	v_mfma_f32_16x16x32_bf16 v[14:17], v[132:135], v[236:239], 0
	v_mfma_f32_16x16x32_bf16 v[14:17], v[142:145], v[240:243], v[14:17]
	s_barrier
	s_setprio 0
	v_add_u32_e32 v170, 0x18000, v140
	v_add_u32_e32 v186, 0x1c000, v140
	ds_read_b128 v[132:135], v170
	ds_read_b128 v[142:145], v170 offset:1024
	ds_read_b128 v[154:157], v170 offset:2048
	ds_read_b128 v[170:173], v170 offset:3072
	ds_read_b128 v[174:177], v186
	ds_read_b128 v[178:181], v186 offset:1024
	ds_read_b128 v[182:185], v186 offset:2048
	ds_read_b128 v[186:189], v186 offset:3072
	s_add_i32 s27, s27, 0x80000
	s_mov_b32 m0, s25
	ds_read_b128 v[190:193], v141 offset:32768
	ds_read_b128 v[194:197], v141 offset:33792
	ds_read_b128 v[198:201], v141 offset:34816
	ds_read_b128 v[202:205], v141 offset:35840
	ds_read_b128 v[228:231], v141 offset:36864
	ds_read_b128 v[232:235], v141 offset:37888
	ds_read_b128 v[236:239], v141 offset:38912
	ds_read_b128 v[240:243], v141 offset:39936
	buffer_load_dwordx4 v136, s[60:63], s27 offen lds
	s_mov_b32 m0, s30
	s_nop 0
	buffer_load_dwordx4 v138, s[60:63], s27 offen lds
	s_waitcnt vmcnt(8)
	s_waitcnt lgkmcnt(0)
	s_setprio 1
	s_barrier
	v_mfma_f32_16x16x32_bf16 v[126:129], v[132:135], v[190:193], v[126:129]
	v_mfma_f32_16x16x32_bf16 v[126:129], v[142:145], v[194:197], v[126:129]
	v_mfma_f32_16x16x32_bf16 v[106:109], v[154:157], v[190:193], v[106:109]
	v_mfma_f32_16x16x32_bf16 v[106:109], v[170:173], v[194:197], v[106:109]
	v_mfma_f32_16x16x32_bf16 v[110:113], v[182:185], v[190:193], v[110:113]
	v_mfma_f32_16x16x32_bf16 v[110:113], v[186:189], v[194:197], v[110:113]
	v_mfma_f32_16x16x32_bf16 v[122:125], v[174:177], v[190:193], v[122:125]
	v_mfma_f32_16x16x32_bf16 v[122:125], v[178:181], v[194:197], v[122:125]
	v_mfma_f32_16x16x32_bf16 v[102:105], v[174:177], v[198:201], v[102:105]
	v_mfma_f32_16x16x32_bf16 v[102:105], v[178:181], v[202:205], v[102:105]
	v_mfma_f32_16x16x32_bf16 v[98:101], v[182:185], v[198:201], v[98:101]
	v_mfma_f32_16x16x32_bf16 v[98:101], v[186:189], v[202:205], v[98:101]
	v_mfma_f32_16x16x32_bf16 v[114:117], v[154:157], v[198:201], v[114:117]
	v_mfma_f32_16x16x32_bf16 v[114:117], v[170:173], v[202:205], v[114:117]
	v_mfma_f32_16x16x32_bf16 v[118:121], v[132:135], v[198:201], v[118:121]
	v_mfma_f32_16x16x32_bf16 v[118:121], v[142:145], v[202:205], v[118:121]
	v_mfma_f32_16x16x32_bf16 v[94:97], v[132:135], v[228:231], v[94:97]
	v_mfma_f32_16x16x32_bf16 v[94:97], v[142:145], v[232:235], v[94:97]
	v_mfma_f32_16x16x32_bf16 v[90:93], v[154:157], v[228:231], v[90:93]
	v_mfma_f32_16x16x32_bf16 v[90:93], v[170:173], v[232:235], v[90:93]
	v_mfma_f32_16x16x32_bf16 v[82:85], v[182:185], v[228:231], v[82:85]
	v_mfma_f32_16x16x32_bf16 v[82:85], v[186:189], v[232:235], v[82:85]
	v_mfma_f32_16x16x32_bf16 v[86:89], v[174:177], v[228:231], v[86:89]
	v_mfma_f32_16x16x32_bf16 v[86:89], v[178:181], v[232:235], v[86:89]
	v_mfma_f32_16x16x32_bf16 v[70:73], v[174:177], v[236:239], v[70:73]
	v_mfma_f32_16x16x32_bf16 v[70:73], v[178:181], v[240:243], v[70:73]
	v_mfma_f32_16x16x32_bf16 v[66:69], v[182:185], v[236:239], v[66:69]
	v_mfma_f32_16x16x32_bf16 v[66:69], v[186:189], v[240:243], v[66:69]
	v_mfma_f32_16x16x32_bf16 v[74:77], v[154:157], v[236:239], v[74:77]
	v_mfma_f32_16x16x32_bf16 v[74:77], v[170:173], v[240:243], v[74:77]
	v_mfma_f32_16x16x32_bf16 v[78:81], v[132:135], v[236:239], v[78:81]
	v_mfma_f32_16x16x32_bf16 v[78:81], v[142:145], v[240:243], v[78:81]
	s_barrier
	s_setprio 0
	s_or_b32 s27, s26, 0x80
	s_mov_b32 m0, s36
	ds_read_b128 v[190:193], v141 offset:49152
	buffer_load_dwordx4 v137, s[44:47], s27 offen lds
	s_add_i32 s26, s26, 0x80080
	s_mov_b32 m0, s37
	ds_read_b128 v[194:197], v141 offset:50176
	buffer_load_dwordx4 v139, s[44:47], s27 offen lds
	s_mov_b32 m0, s68
	ds_read_b128 v[198:201], v141 offset:51200
	buffer_load_dwordx4 v137, s[44:47], s26 offen lds
	s_mov_b32 m0, s69
	ds_read_b128 v[202:205], v141 offset:52224
	buffer_load_dwordx4 v139, s[44:47], s26 offen lds
	s_mov_b32 m0, s66
	ds_read_b128 v[228:231], v141 offset:53248
	buffer_load_dwordx4 v136, s[60:63], s23 offen lds
	s_mov_b32 m0, s67
	ds_read_b128 v[232:235], v141 offset:54272
	buffer_load_dwordx4 v138, s[60:63], s23 offen lds
	ds_read_b128 v[236:239], v141 offset:55296
	ds_read_b128 v[240:243], v141 offset:56320
	s_waitcnt vmcnt(8)
	s_waitcnt lgkmcnt(0)
	s_setprio 1
	s_barrier
	v_mfma_f32_16x16x32_bf16 v[62:65], v[132:135], v[190:193], v[62:65]
	v_mfma_f32_16x16x32_bf16 v[62:65], v[142:145], v[194:197], v[62:65]
	v_mfma_f32_16x16x32_bf16 v[58:61], v[154:157], v[190:193], v[58:61]
	v_mfma_f32_16x16x32_bf16 v[58:61], v[170:173], v[194:197], v[58:61]
	v_mfma_f32_16x16x32_bf16 v[50:53], v[182:185], v[190:193], v[50:53]
	v_mfma_f32_16x16x32_bf16 v[50:53], v[186:189], v[194:197], v[50:53]
	v_mfma_f32_16x16x32_bf16 v[54:57], v[174:177], v[190:193], v[54:57]
	v_mfma_f32_16x16x32_bf16 v[54:57], v[178:181], v[194:197], v[54:57]
	v_mfma_f32_16x16x32_bf16 v[38:41], v[174:177], v[198:201], v[38:41]
	v_mfma_f32_16x16x32_bf16 v[38:41], v[178:181], v[202:205], v[38:41]
	v_mfma_f32_16x16x32_bf16 v[34:37], v[182:185], v[198:201], v[34:37]
	v_mfma_f32_16x16x32_bf16 v[34:37], v[186:189], v[202:205], v[34:37]
	v_mfma_f32_16x16x32_bf16 v[42:45], v[154:157], v[198:201], v[42:45]
	v_mfma_f32_16x16x32_bf16 v[42:45], v[170:173], v[202:205], v[42:45]
	v_mfma_f32_16x16x32_bf16 v[46:49], v[132:135], v[198:201], v[46:49]
	v_mfma_f32_16x16x32_bf16 v[46:49], v[142:145], v[202:205], v[46:49]
	v_mfma_f32_16x16x32_bf16 v[30:33], v[132:135], v[228:231], v[30:33]
	v_mfma_f32_16x16x32_bf16 v[30:33], v[142:145], v[232:235], v[30:33]
	v_mfma_f32_16x16x32_bf16 v[26:29], v[154:157], v[228:231], v[26:29]
	v_mfma_f32_16x16x32_bf16 v[26:29], v[170:173], v[232:235], v[26:29]
	v_mfma_f32_16x16x32_bf16 v[18:21], v[182:185], v[228:231], v[18:21]
	v_mfma_f32_16x16x32_bf16 v[18:21], v[186:189], v[232:235], v[18:21]
	v_mfma_f32_16x16x32_bf16 v[22:25], v[174:177], v[228:231], v[22:25]
	v_mfma_f32_16x16x32_bf16 v[22:25], v[178:181], v[232:235], v[22:25]
	v_mfma_f32_16x16x32_bf16 v[6:9], v[174:177], v[236:239], v[6:9]
	v_mfma_f32_16x16x32_bf16 v[6:9], v[178:181], v[240:243], v[6:9]
	v_mfma_f32_16x16x32_bf16 v[2:5], v[182:185], v[236:239], v[2:5]
	v_mfma_f32_16x16x32_bf16 v[2:5], v[186:189], v[240:243], v[2:5]
	v_mfma_f32_16x16x32_bf16 v[10:13], v[154:157], v[236:239], v[10:13]
	v_mfma_f32_16x16x32_bf16 v[10:13], v[170:173], v[240:243], v[10:13]
	v_mfma_f32_16x16x32_bf16 v[14:17], v[132:135], v[236:239], v[14:17]
	v_mfma_f32_16x16x32_bf16 v[14:17], v[142:145], v[240:243], v[14:17]
	s_barrier
	s_setprio 0
	s_add_i32 s22, s22, 2
	s_addk_i32 s13, 0x100
	s_addk_i32 s21, 0x100
	s_cmp_gt_u32 s22, 29

.LBB0_2155:
	s_mul_i32 s49, s48, 0x2c0000
	s_and_b64 s[8:9], s[42:43], exec
	s_mul_i32 s23, s15, 0x2c0000
	s_cselect_b32 s8, s49, s21
	s_cselect_b32 s9, s23, s13
	s_addk_i32 s13, 0x100
	s_add_i32 s21, s21, 0xc000
	s_mov_b32 s22, -2
	s_waitcnt lgkmcnt(0)
	v_add_u32_e32 v170, 0x10000, v140
	v_add_u32_e32 v186, 0x14000, v140
	ds_read_b128 v[132:135], v170
	ds_read_b128 v[142:145], v170 offset:1024
	ds_read_b128 v[154:157], v170 offset:2048
	ds_read_b128 v[170:173], v170 offset:3072
	ds_read_b128 v[174:177], v186
	ds_read_b128 v[178:181], v186 offset:1024
	ds_read_b128 v[182:185], v186 offset:2048
	ds_read_b128 v[186:189], v186 offset:3072
	s_add_i32 s26, s21, 0x4000
	s_cmpk_eq_i32 s22, 0x54
	s_cselect_b32 s52, s8, s26
	s_cselect_b32 s27, s9, s13
	s_or_b32 s26, s52, 0x8000
	s_mov_b32 m0, s84
	ds_read_b128 v[190:193], v141
	ds_read_b128 v[194:197], v141 offset:1024
	ds_read_b128 v[198:201], v141 offset:2048
	ds_read_b128 v[202:205], v141 offset:3072
	ds_read_b128 v[228:231], v141 offset:4096
	ds_read_b128 v[232:235], v141 offset:5120
	ds_read_b128 v[236:239], v141 offset:6144
	ds_read_b128 v[240:243], v141 offset:7168
	buffer_load_dwordx4 v136, s[60:63], s21 offen lds
	s_mov_b32 m0, s16
	s_nop 0
	buffer_load_dwordx4 v138, s[60:63], s21 offen lds
	s_waitcnt vmcnt(32)
	s_waitcnt lgkmcnt(0)
	s_setprio 1
	s_barrier
	v_mfma_f32_16x16x32_bf16 v[126:129], v[132:135], v[190:193], 0
	v_mfma_f32_16x16x32_bf16 v[126:129], v[142:145], v[194:197], v[126:129]
	v_mfma_f32_16x16x32_bf16 v[106:109], v[154:157], v[190:193], 0
	v_mfma_f32_16x16x32_bf16 v[106:109], v[170:173], v[194:197], v[106:109]
	v_mfma_f32_16x16x32_bf16 v[110:113], v[182:185], v[190:193], 0
	v_mfma_f32_16x16x32_bf16 v[110:113], v[186:189], v[194:197], v[110:113]
	v_mfma_f32_16x16x32_bf16 v[122:125], v[174:177], v[190:193], 0
	v_mfma_f32_16x16x32_bf16 v[122:125], v[178:181], v[194:197], v[122:125]
	v_mfma_f32_16x16x32_bf16 v[102:105], v[174:177], v[198:201], 0
	v_mfma_f32_16x16x32_bf16 v[102:105], v[178:181], v[202:205], v[102:105]
	v_mfma_f32_16x16x32_bf16 v[98:101], v[182:185], v[198:201], 0
	v_mfma_f32_16x16x32_bf16 v[98:101], v[186:189], v[202:205], v[98:101]
	v_mfma_f32_16x16x32_bf16 v[114:117], v[154:157], v[198:201], 0
	v_mfma_f32_16x16x32_bf16 v[114:117], v[170:173], v[202:205], v[114:117]
	v_mfma_f32_16x16x32_bf16 v[118:121], v[132:135], v[198:201], 0
	v_mfma_f32_16x16x32_bf16 v[118:121], v[142:145], v[202:205], v[118:121]
	v_mfma_f32_16x16x32_bf16 v[94:97], v[132:135], v[228:231], 0
	v_mfma_f32_16x16x32_bf16 v[94:97], v[142:145], v[232:235], v[94:97]
	v_mfma_f32_16x16x32_bf16 v[90:93], v[154:157], v[228:231], 0
	v_mfma_f32_16x16x32_bf16 v[90:93], v[170:173], v[232:235], v[90:93]
	v_mfma_f32_16x16x32_bf16 v[82:85], v[182:185], v[228:231], 0
	v_mfma_f32_16x16x32_bf16 v[82:85], v[186:189], v[232:235], v[82:85]
	v_mfma_f32_16x16x32_bf16 v[86:89], v[174:177], v[228:231], 0
	v_mfma_f32_16x16x32_bf16 v[86:89], v[178:181], v[232:235], v[86:89]
	v_mfma_f32_16x16x32_bf16 v[70:73], v[174:177], v[236:239], 0
	v_mfma_f32_16x16x32_bf16 v[70:73], v[178:181], v[240:243], v[70:73]
	v_mfma_f32_16x16x32_bf16 v[66:69], v[182:185], v[236:239], 0
	v_mfma_f32_16x16x32_bf16 v[66:69], v[186:189], v[240:243], v[66:69]
	v_mfma_f32_16x16x32_bf16 v[74:77], v[154:157], v[236:239], 0
	v_mfma_f32_16x16x32_bf16 v[74:77], v[170:173], v[240:243], v[74:77]
	v_mfma_f32_16x16x32_bf16 v[78:81], v[132:135], v[236:239], 0
	v_mfma_f32_16x16x32_bf16 v[78:81], v[142:145], v[240:243], v[78:81]
	s_barrier
	s_setprio 0
	s_mov_b32 s46, s62
	s_mov_b32 s47, s63
	s_mov_b32 m0, s18
	ds_read_b128 v[190:193], v141 offset:16384
	buffer_load_dwordx4 v137, s[44:47], s27 offen lds
	s_add_i32 s53, s27, 0x160000
	s_mov_b32 m0, s19
	ds_read_b128 v[194:197], v141 offset:17408
	buffer_load_dwordx4 v139, s[44:47], s27 offen lds
	s_mov_b32 m0, s24
	ds_read_b128 v[198:201], v141 offset:18432
	buffer_load_dwordx4 v137, s[44:47], s53 offen lds
	s_mov_b32 m0, s25
	ds_read_b128 v[202:205], v141 offset:19456
	buffer_load_dwordx4 v139, s[44:47], s53 offen lds
	s_mov_b32 m0, s14
	ds_read_b128 v[228:231], v141 offset:20480
	buffer_load_dwordx4 v136, s[60:63], s52 offen lds
	s_mov_b32 m0, s30
	ds_read_b128 v[232:235], v141 offset:21504
	buffer_load_dwordx4 v138, s[60:63], s52 offen lds
	ds_read_b128 v[236:239], v141 offset:22528
	ds_read_b128 v[240:243], v141 offset:23552
	s_cmp_lg_u32 s85, 1
	s_cbranch_scc1 .Lgk_w2_2
	s_waitcnt vmcnt(8)
.Lgk_w2_2:
	s_waitcnt lgkmcnt(0)
	s_setprio 1
	s_barrier
	v_mfma_f32_16x16x32_bf16 v[62:65], v[132:135], v[190:193], 0
	v_mfma_f32_16x16x32_bf16 v[62:65], v[142:145], v[194:197], v[62:65]
	v_mfma_f32_16x16x32_bf16 v[58:61], v[154:157], v[190:193], 0
	v_mfma_f32_16x16x32_bf16 v[58:61], v[170:173], v[194:197], v[58:61]
	v_mfma_f32_16x16x32_bf16 v[50:53], v[182:185], v[190:193], 0
	v_mfma_f32_16x16x32_bf16 v[50:53], v[186:189], v[194:197], v[50:53]
	v_mfma_f32_16x16x32_bf16 v[54:57], v[174:177], v[190:193], 0
	v_mfma_f32_16x16x32_bf16 v[54:57], v[178:181], v[194:197], v[54:57]
	v_mfma_f32_16x16x32_bf16 v[38:41], v[174:177], v[198:201], 0
	v_mfma_f32_16x16x32_bf16 v[38:41], v[178:181], v[202:205], v[38:41]
	v_mfma_f32_16x16x32_bf16 v[34:37], v[182:185], v[198:201], 0
	v_mfma_f32_16x16x32_bf16 v[34:37], v[186:189], v[202:205], v[34:37]
	v_mfma_f32_16x16x32_bf16 v[42:45], v[154:157], v[198:201], 0
	v_mfma_f32_16x16x32_bf16 v[42:45], v[170:173], v[202:205], v[42:45]
	v_mfma_f32_16x16x32_bf16 v[46:49], v[132:135], v[198:201], 0
	v_mfma_f32_16x16x32_bf16 v[46:49], v[142:145], v[202:205], v[46:49]
	v_mfma_f32_16x16x32_bf16 v[30:33], v[132:135], v[228:231], 0
	v_mfma_f32_16x16x32_bf16 v[30:33], v[142:145], v[232:235], v[30:33]
	v_mfma_f32_16x16x32_bf16 v[26:29], v[154:157], v[228:231], 0
	v_mfma_f32_16x16x32_bf16 v[26:29], v[170:173], v[232:235], v[26:29]
	v_mfma_f32_16x16x32_bf16 v[18:21], v[182:185], v[228:231], 0
	v_mfma_f32_16x16x32_bf16 v[18:21], v[186:189], v[232:235], v[18:21]
	v_mfma_f32_16x16x32_bf16 v[22:25], v[174:177], v[228:231], 0
	v_mfma_f32_16x16x32_bf16 v[22:25], v[178:181], v[232:235], v[22:25]
	v_mfma_f32_16x16x32_bf16 v[6:9], v[174:177], v[236:239], 0
	v_mfma_f32_16x16x32_bf16 v[6:9], v[178:181], v[240:243], v[6:9]
	v_mfma_f32_16x16x32_bf16 v[2:5], v[182:185], v[236:239], 0
	v_mfma_f32_16x16x32_bf16 v[2:5], v[186:189], v[240:243], v[2:5]
	v_mfma_f32_16x16x32_bf16 v[10:13], v[154:157], v[236:239], 0
	v_mfma_f32_16x16x32_bf16 v[10:13], v[170:173], v[240:243], v[10:13]
	v_mfma_f32_16x16x32_bf16 v[14:17], v[132:135], v[236:239], 0
	v_mfma_f32_16x16x32_bf16 v[14:17], v[142:145], v[240:243], v[14:17]
	s_barrier
	s_setprio 0
	v_add_u32_e32 v170, 0x18000, v140
	v_add_u32_e32 v186, 0x1c000, v140
	ds_read_b128 v[132:135], v170
	ds_read_b128 v[142:145], v170 offset:1024
	ds_read_b128 v[154:157], v170 offset:2048
	ds_read_b128 v[170:173], v170 offset:3072
	ds_read_b128 v[174:177], v186
	ds_read_b128 v[178:181], v186 offset:1024
	ds_read_b128 v[182:185], v186 offset:2048
	ds_read_b128 v[186:189], v186 offset:3072
	s_bitset1_b32 s52, 14
	s_mov_b32 m0, s31
	ds_read_b128 v[190:193], v141 offset:32768
	ds_read_b128 v[194:197], v141 offset:33792
	ds_read_b128 v[198:201], v141 offset:34816
	ds_read_b128 v[202:205], v141 offset:35840
	ds_read_b128 v[228:231], v141 offset:36864
	ds_read_b128 v[232:235], v141 offset:37888
	ds_read_b128 v[236:239], v141 offset:38912
	ds_read_b128 v[240:243], v141 offset:39936
	buffer_load_dwordx4 v136, s[60:63], s52 offen lds
	s_mov_b32 m0, s33
	s_nop 0
	buffer_load_dwordx4 v138, s[60:63], s52 offen lds
	s_waitcnt vmcnt(8)
	s_waitcnt lgkmcnt(0)
	s_setprio 1
	s_barrier
	v_mfma_f32_16x16x32_bf16 v[126:129], v[132:135], v[190:193], v[126:129]
	v_mfma_f32_16x16x32_bf16 v[126:129], v[142:145], v[194:197], v[126:129]
	v_mfma_f32_16x16x32_bf16 v[106:109], v[154:157], v[190:193], v[106:109]
	v_mfma_f32_16x16x32_bf16 v[106:109], v[170:173], v[194:197], v[106:109]
	v_mfma_f32_16x16x32_bf16 v[110:113], v[182:185], v[190:193], v[110:113]
	v_mfma_f32_16x16x32_bf16 v[110:113], v[186:189], v[194:197], v[110:113]
	v_mfma_f32_16x16x32_bf16 v[122:125], v[174:177], v[190:193], v[122:125]
	v_mfma_f32_16x16x32_bf16 v[122:125], v[178:181], v[194:197], v[122:125]
	v_mfma_f32_16x16x32_bf16 v[102:105], v[174:177], v[198:201], v[102:105]
	v_mfma_f32_16x16x32_bf16 v[102:105], v[178:181], v[202:205], v[102:105]
	v_mfma_f32_16x16x32_bf16 v[98:101], v[182:185], v[198:201], v[98:101]
	v_mfma_f32_16x16x32_bf16 v[98:101], v[186:189], v[202:205], v[98:101]
	v_mfma_f32_16x16x32_bf16 v[114:117], v[154:157], v[198:201], v[114:117]
	v_mfma_f32_16x16x32_bf16 v[114:117], v[170:173], v[202:205], v[114:117]
	v_mfma_f32_16x16x32_bf16 v[118:121], v[132:135], v[198:201], v[118:121]
	v_mfma_f32_16x16x32_bf16 v[118:121], v[142:145], v[202:205], v[118:121]
	v_mfma_f32_16x16x32_bf16 v[94:97], v[132:135], v[228:231], v[94:97]
	v_mfma_f32_16x16x32_bf16 v[94:97], v[142:145], v[232:235], v[94:97]
	v_mfma_f32_16x16x32_bf16 v[90:93], v[154:157], v[228:231], v[90:93]
	v_mfma_f32_16x16x32_bf16 v[90:93], v[170:173], v[232:235], v[90:93]
	v_mfma_f32_16x16x32_bf16 v[82:85], v[182:185], v[228:231], v[82:85]
	v_mfma_f32_16x16x32_bf16 v[82:85], v[186:189], v[232:235], v[82:85]
	v_mfma_f32_16x16x32_bf16 v[86:89], v[174:177], v[228:231], v[86:89]
	v_mfma_f32_16x16x32_bf16 v[86:89], v[178:181], v[232:235], v[86:89]
	v_mfma_f32_16x16x32_bf16 v[70:73], v[174:177], v[236:239], v[70:73]
	v_mfma_f32_16x16x32_bf16 v[70:73], v[178:181], v[240:243], v[70:73]
	v_mfma_f32_16x16x32_bf16 v[66:69], v[182:185], v[236:239], v[66:69]
	v_mfma_f32_16x16x32_bf16 v[66:69], v[186:189], v[240:243], v[66:69]
	v_mfma_f32_16x16x32_bf16 v[74:77], v[154:157], v[236:239], v[74:77]
	v_mfma_f32_16x16x32_bf16 v[74:77], v[170:173], v[240:243], v[74:77]
	v_mfma_f32_16x16x32_bf16 v[78:81], v[132:135], v[236:239], v[78:81]
	v_mfma_f32_16x16x32_bf16 v[78:81], v[142:145], v[240:243], v[78:81]
	s_barrier
	s_setprio 0
	s_or_b32 s52, s27, 0x80
	s_mov_b32 m0, s68
	ds_read_b128 v[190:193], v141 offset:49152
	buffer_load_dwordx4 v137, s[44:47], s52 offen lds
	s_add_i32 s27, s27, 0x160080
	s_mov_b32 m0, s69
	ds_read_b128 v[194:197], v141 offset:50176
	buffer_load_dwordx4 v139, s[44:47], s52 offen lds
	s_mov_b32 m0, s72
	ds_read_b128 v[198:201], v141 offset:51200
	buffer_load_dwordx4 v137, s[44:47], s27 offen lds
	s_mov_b32 m0, s73
	ds_read_b128 v[202:205], v141 offset:52224
	buffer_load_dwordx4 v139, s[44:47], s27 offen lds
	s_mov_b32 m0, s70
	ds_read_b128 v[228:231], v141 offset:53248
	buffer_load_dwordx4 v136, s[60:63], s26 offen lds
	s_mov_b32 m0, s71
	ds_read_b128 v[232:235], v141 offset:54272
	buffer_load_dwordx4 v138, s[60:63], s26 offen lds
	ds_read_b128 v[236:239], v141 offset:55296
	ds_read_b128 v[240:243], v141 offset:56320
	s_waitcnt vmcnt(8)
	s_waitcnt lgkmcnt(0)
	s_setprio 1
	s_barrier
	v_mfma_f32_16x16x32_bf16 v[62:65], v[132:135], v[190:193], v[62:65]
	v_mfma_f32_16x16x32_bf16 v[62:65], v[142:145], v[194:197], v[62:65]
	v_mfma_f32_16x16x32_bf16 v[58:61], v[154:157], v[190:193], v[58:61]
	v_mfma_f32_16x16x32_bf16 v[58:61], v[170:173], v[194:197], v[58:61]
	v_mfma_f32_16x16x32_bf16 v[50:53], v[182:185], v[190:193], v[50:53]
	v_mfma_f32_16x16x32_bf16 v[50:53], v[186:189], v[194:197], v[50:53]
	v_mfma_f32_16x16x32_bf16 v[54:57], v[174:177], v[190:193], v[54:57]
	v_mfma_f32_16x16x32_bf16 v[54:57], v[178:181], v[194:197], v[54:57]
	v_mfma_f32_16x16x32_bf16 v[38:41], v[174:177], v[198:201], v[38:41]
	v_mfma_f32_16x16x32_bf16 v[38:41], v[178:181], v[202:205], v[38:41]
	v_mfma_f32_16x16x32_bf16 v[34:37], v[182:185], v[198:201], v[34:37]
	v_mfma_f32_16x16x32_bf16 v[34:37], v[186:189], v[202:205], v[34:37]
	v_mfma_f32_16x16x32_bf16 v[42:45], v[154:157], v[198:201], v[42:45]
	v_mfma_f32_16x16x32_bf16 v[42:45], v[170:173], v[202:205], v[42:45]
	v_mfma_f32_16x16x32_bf16 v[46:49], v[132:135], v[198:201], v[46:49]
	v_mfma_f32_16x16x32_bf16 v[46:49], v[142:145], v[202:205], v[46:49]
	v_mfma_f32_16x16x32_bf16 v[30:33], v[132:135], v[228:231], v[30:33]
	v_mfma_f32_16x16x32_bf16 v[30:33], v[142:145], v[232:235], v[30:33]
	v_mfma_f32_16x16x32_bf16 v[26:29], v[154:157], v[228:231], v[26:29]
	v_mfma_f32_16x16x32_bf16 v[26:29], v[170:173], v[232:235], v[26:29]
	v_mfma_f32_16x16x32_bf16 v[18:21], v[182:185], v[228:231], v[18:21]
	v_mfma_f32_16x16x32_bf16 v[18:21], v[186:189], v[232:235], v[18:21]
	v_mfma_f32_16x16x32_bf16 v[22:25], v[174:177], v[228:231], v[22:25]
	v_mfma_f32_16x16x32_bf16 v[22:25], v[178:181], v[232:235], v[22:25]
	v_mfma_f32_16x16x32_bf16 v[6:9], v[174:177], v[236:239], v[6:9]
	v_mfma_f32_16x16x32_bf16 v[6:9], v[178:181], v[240:243], v[6:9]
	v_mfma_f32_16x16x32_bf16 v[2:5], v[182:185], v[236:239], v[2:5]
	v_mfma_f32_16x16x32_bf16 v[2:5], v[186:189], v[240:243], v[2:5]
	v_mfma_f32_16x16x32_bf16 v[10:13], v[154:157], v[236:239], v[10:13]
	v_mfma_f32_16x16x32_bf16 v[10:13], v[170:173], v[240:243], v[10:13]
	v_mfma_f32_16x16x32_bf16 v[14:17], v[132:135], v[236:239], v[14:17]
	v_mfma_f32_16x16x32_bf16 v[14:17], v[142:145], v[240:243], v[14:17]
	s_barrier
	s_setprio 0
	s_addk_i32 s13, 0x100
	s_add_i32 s22, s22, 2
	s_add_i32 s21, s21, 0x10000
	s_cmpk_gt_u32 s22, 0x55

.LBB0_2449:
	s_lshl_b32 s73, s72, 20
	s_and_b64 s[8:9], s[40:41], exec
	s_cselect_b32 s8, s73, s13
	s_lshl_b32 s84, s71, 20
	s_and_b64 s[24:25], s[40:41], exec
	s_cselect_b32 s9, s84, s21
	s_add_i32 s13, s13, 0x80080
	s_addk_i32 s21, 0x100
	s_mov_b32 s22, -2
	s_waitcnt lgkmcnt(0)
	v_add_u32_e32 v142, 0x10000, v188
	v_add_u32_e32 v182, 0x14000, v188
	ds_read_b128 v[130:133], v142
	ds_read_b128 v[134:137], v142 offset:1024
	ds_read_b128 v[138:141], v142 offset:2048
	ds_read_b128 v[142:145], v142 offset:3072
	ds_read_b128 v[154:157], v182
	ds_read_b128 v[174:177], v182 offset:1024
	ds_read_b128 v[178:181], v182 offset:2048
	ds_read_b128 v[190:193], v182 offset:3072
	s_add_i32 s24, s13, 0xfff80080
	s_cmp_eq_u32 s22, 28
	s_cselect_b32 s52, s8, s24
	s_cselect_b32 s25, s9, s21
	s_or_b32 s24, s52, 0x80
	s_mov_b32 m0, s68
	ds_read_b128 v[194:197], v189
	ds_read_b128 v[198:201], v189 offset:1024
	ds_read_b128 v[202:205], v189 offset:2048
	ds_read_b128 v[228:231], v189 offset:3072
	ds_read_b128 v[232:235], v189 offset:4096
	ds_read_b128 v[236:239], v189 offset:5120
	ds_read_b128 v[240:243], v189 offset:6144
	ds_read_b128 v[244:247], v189 offset:7168
	buffer_load_dwordx4 v184, s[60:63], s13 offen lds
	s_mov_b32 m0, s70
	s_nop 0
	buffer_load_dwordx4 v186, s[60:63], s13 offen lds
	s_waitcnt vmcnt(32)
	s_waitcnt lgkmcnt(0)
	s_setprio 1
	s_barrier
	v_mfma_f32_16x16x32_bf16 v[126:129], v[130:133], v[194:197], 0
	v_mfma_f32_16x16x32_bf16 v[126:129], v[134:137], v[198:201], v[126:129]
	v_mfma_f32_16x16x32_bf16 v[122:125], v[138:141], v[194:197], 0
	v_mfma_f32_16x16x32_bf16 v[122:125], v[142:145], v[198:201], v[122:125]
	v_mfma_f32_16x16x32_bf16 v[114:117], v[178:181], v[194:197], 0
	v_mfma_f32_16x16x32_bf16 v[114:117], v[190:193], v[198:201], v[114:117]
	v_mfma_f32_16x16x32_bf16 v[118:121], v[154:157], v[194:197], 0
	v_mfma_f32_16x16x32_bf16 v[118:121], v[174:177], v[198:201], v[118:121]
	v_mfma_f32_16x16x32_bf16 v[102:105], v[154:157], v[202:205], 0
	v_mfma_f32_16x16x32_bf16 v[102:105], v[174:177], v[228:231], v[102:105]
	v_mfma_f32_16x16x32_bf16 v[98:101], v[178:181], v[202:205], 0
	v_mfma_f32_16x16x32_bf16 v[98:101], v[190:193], v[228:231], v[98:101]
	v_mfma_f32_16x16x32_bf16 v[106:109], v[138:141], v[202:205], 0
	v_mfma_f32_16x16x32_bf16 v[106:109], v[142:145], v[228:231], v[106:109]
	v_mfma_f32_16x16x32_bf16 v[110:113], v[130:133], v[202:205], 0
	v_mfma_f32_16x16x32_bf16 v[110:113], v[134:137], v[228:231], v[110:113]
	v_mfma_f32_16x16x32_bf16 v[94:97], v[130:133], v[232:235], 0
	v_mfma_f32_16x16x32_bf16 v[94:97], v[134:137], v[236:239], v[94:97]
	v_mfma_f32_16x16x32_bf16 v[90:93], v[138:141], v[232:235], 0
	v_mfma_f32_16x16x32_bf16 v[90:93], v[142:145], v[236:239], v[90:93]
	v_mfma_f32_16x16x32_bf16 v[82:85], v[178:181], v[232:235], 0
	v_mfma_f32_16x16x32_bf16 v[82:85], v[190:193], v[236:239], v[82:85]
	v_mfma_f32_16x16x32_bf16 v[86:89], v[154:157], v[232:235], 0
	v_mfma_f32_16x16x32_bf16 v[86:89], v[174:177], v[236:239], v[86:89]
	v_mfma_f32_16x16x32_bf16 v[70:73], v[154:157], v[240:243], 0
	v_mfma_f32_16x16x32_bf16 v[70:73], v[174:177], v[244:247], v[70:73]
	v_mfma_f32_16x16x32_bf16 v[66:69], v[178:181], v[240:243], 0
	v_mfma_f32_16x16x32_bf16 v[66:69], v[190:193], v[244:247], v[66:69]
	v_mfma_f32_16x16x32_bf16 v[74:77], v[138:141], v[240:243], 0
	v_mfma_f32_16x16x32_bf16 v[74:77], v[142:145], v[244:247], v[74:77]
	v_mfma_f32_16x16x32_bf16 v[78:81], v[130:133], v[240:243], 0
	v_mfma_f32_16x16x32_bf16 v[78:81], v[134:137], v[244:247], v[78:81]
	s_barrier
	s_setprio 0
	s_mov_b32 s46, s62
	s_mov_b32 s47, s63
	s_mov_b32 m0, s16
	ds_read_b128 v[194:197], v189 offset:16384
	buffer_load_dwordx4 v185, s[44:47], s25 offen lds
	s_add_i32 s53, s25, 0x80000
	s_mov_b32 m0, s18
	ds_read_b128 v[198:201], v189 offset:17408
	buffer_load_dwordx4 v187, s[44:47], s25 offen lds
	s_mov_b32 m0, s19
	ds_read_b128 v[202:205], v189 offset:18432
	buffer_load_dwordx4 v185, s[44:47], s53 offen lds
	s_mov_b32 m0, s23
	ds_read_b128 v[228:231], v189 offset:19456
	buffer_load_dwordx4 v187, s[44:47], s53 offen lds
	s_mov_b32 m0, s15
	ds_read_b128 v[232:235], v189 offset:20480
	buffer_load_dwordx4 v184, s[60:63], s52 offen lds
	s_mov_b32 m0, s26
	ds_read_b128 v[236:239], v189 offset:21504
	buffer_load_dwordx4 v186, s[60:63], s52 offen lds
	ds_read_b128 v[240:243], v189 offset:22528
	ds_read_b128 v[244:247], v189 offset:23552
	s_cmp_lg_u32 s69, 1
	s_cbranch_scc1 .Lgk_w2_3
	s_waitcnt vmcnt(8)
.Lgk_w2_3:
	s_waitcnt lgkmcnt(0)
	s_setprio 1
	s_barrier
	v_mfma_f32_16x16x32_bf16 v[62:65], v[130:133], v[194:197], 0
	v_mfma_f32_16x16x32_bf16 v[62:65], v[134:137], v[198:201], v[62:65]
	v_mfma_f32_16x16x32_bf16 v[58:61], v[138:141], v[194:197], 0
	v_mfma_f32_16x16x32_bf16 v[58:61], v[142:145], v[198:201], v[58:61]
	v_mfma_f32_16x16x32_bf16 v[50:53], v[178:181], v[194:197], 0
	v_mfma_f32_16x16x32_bf16 v[50:53], v[190:193], v[198:201], v[50:53]
	v_mfma_f32_16x16x32_bf16 v[54:57], v[154:157], v[194:197], 0
	v_mfma_f32_16x16x32_bf16 v[54:57], v[174:177], v[198:201], v[54:57]
	v_mfma_f32_16x16x32_bf16 v[38:41], v[154:157], v[202:205], 0
	v_mfma_f32_16x16x32_bf16 v[38:41], v[174:177], v[228:231], v[38:41]
	v_mfma_f32_16x16x32_bf16 v[34:37], v[178:181], v[202:205], 0
	v_mfma_f32_16x16x32_bf16 v[34:37], v[190:193], v[228:231], v[34:37]
	v_mfma_f32_16x16x32_bf16 v[42:45], v[138:141], v[202:205], 0
	v_mfma_f32_16x16x32_bf16 v[42:45], v[142:145], v[228:231], v[42:45]
	v_mfma_f32_16x16x32_bf16 v[46:49], v[130:133], v[202:205], 0
	v_mfma_f32_16x16x32_bf16 v[46:49], v[134:137], v[228:231], v[46:49]
	v_mfma_f32_16x16x32_bf16 v[30:33], v[130:133], v[232:235], 0
	v_mfma_f32_16x16x32_bf16 v[30:33], v[134:137], v[236:239], v[30:33]
	v_mfma_f32_16x16x32_bf16 v[26:29], v[138:141], v[232:235], 0
	v_mfma_f32_16x16x32_bf16 v[26:29], v[142:145], v[236:239], v[26:29]
	v_mfma_f32_16x16x32_bf16 v[18:21], v[178:181], v[232:235], 0
	v_mfma_f32_16x16x32_bf16 v[18:21], v[190:193], v[236:239], v[18:21]
	v_mfma_f32_16x16x32_bf16 v[22:25], v[154:157], v[232:235], 0
	v_mfma_f32_16x16x32_bf16 v[22:25], v[174:177], v[236:239], v[22:25]
	v_mfma_f32_16x16x32_bf16 v[6:9], v[154:157], v[240:243], 0
	v_mfma_f32_16x16x32_bf16 v[6:9], v[174:177], v[244:247], v[6:9]
	v_mfma_f32_16x16x32_bf16 v[2:5], v[178:181], v[240:243], 0
	v_mfma_f32_16x16x32_bf16 v[2:5], v[190:193], v[244:247], v[2:5]
	v_mfma_f32_16x16x32_bf16 v[10:13], v[138:141], v[240:243], 0
	v_mfma_f32_16x16x32_bf16 v[10:13], v[142:145], v[244:247], v[10:13]
	v_mfma_f32_16x16x32_bf16 v[14:17], v[130:133], v[240:243], 0
	v_mfma_f32_16x16x32_bf16 v[14:17], v[134:137], v[244:247], v[14:17]
	s_barrier
	s_setprio 0
	v_add_u32_e32 v142, 0x18000, v188
	v_add_u32_e32 v182, 0x1c000, v188
	ds_read_b128 v[130:133], v142
	ds_read_b128 v[134:137], v142 offset:1024
	ds_read_b128 v[138:141], v142 offset:2048
	ds_read_b128 v[142:145], v142 offset:3072
	ds_read_b128 v[154:157], v182
	ds_read_b128 v[174:177], v182 offset:1024
	ds_read_b128 v[178:181], v182 offset:2048
	ds_read_b128 v[190:193], v182 offset:3072
	s_add_i32 s52, s52, 0x80000
	s_mov_b32 m0, s27
	ds_read_b128 v[194:197], v189 offset:32768
	ds_read_b128 v[198:201], v189 offset:33792
	ds_read_b128 v[202:205], v189 offset:34816
	ds_read_b128 v[228:231], v189 offset:35840
	ds_read_b128 v[232:235], v189 offset:36864
	ds_read_b128 v[236:239], v189 offset:37888
	ds_read_b128 v[240:243], v189 offset:38912
	ds_read_b128 v[244:247], v189 offset:39936
	buffer_load_dwordx4 v184, s[60:63], s52 offen lds
	s_mov_b32 m0, s30
	s_nop 0
	buffer_load_dwordx4 v186, s[60:63], s52 offen lds
	s_waitcnt vmcnt(8)
	s_waitcnt lgkmcnt(0)
	s_setprio 1
	s_barrier
	v_mfma_f32_16x16x32_bf16 v[126:129], v[130:133], v[194:197], v[126:129]
	v_mfma_f32_16x16x32_bf16 v[126:129], v[134:137], v[198:201], v[126:129]
	v_mfma_f32_16x16x32_bf16 v[122:125], v[138:141], v[194:197], v[122:125]
	v_mfma_f32_16x16x32_bf16 v[122:125], v[142:145], v[198:201], v[122:125]
	v_mfma_f32_16x16x32_bf16 v[114:117], v[178:181], v[194:197], v[114:117]
	v_mfma_f32_16x16x32_bf16 v[114:117], v[190:193], v[198:201], v[114:117]
	v_mfma_f32_16x16x32_bf16 v[118:121], v[154:157], v[194:197], v[118:121]
	v_mfma_f32_16x16x32_bf16 v[118:121], v[174:177], v[198:201], v[118:121]
	v_mfma_f32_16x16x32_bf16 v[102:105], v[154:157], v[202:205], v[102:105]
	v_mfma_f32_16x16x32_bf16 v[102:105], v[174:177], v[228:231], v[102:105]
	v_mfma_f32_16x16x32_bf16 v[98:101], v[178:181], v[202:205], v[98:101]
	v_mfma_f32_16x16x32_bf16 v[98:101], v[190:193], v[228:231], v[98:101]
	v_mfma_f32_16x16x32_bf16 v[106:109], v[138:141], v[202:205], v[106:109]
	v_mfma_f32_16x16x32_bf16 v[106:109], v[142:145], v[228:231], v[106:109]
	v_mfma_f32_16x16x32_bf16 v[110:113], v[130:133], v[202:205], v[110:113]
	v_mfma_f32_16x16x32_bf16 v[110:113], v[134:137], v[228:231], v[110:113]
	v_mfma_f32_16x16x32_bf16 v[94:97], v[130:133], v[232:235], v[94:97]
	v_mfma_f32_16x16x32_bf16 v[94:97], v[134:137], v[236:239], v[94:97]
	v_mfma_f32_16x16x32_bf16 v[90:93], v[138:141], v[232:235], v[90:93]
	v_mfma_f32_16x16x32_bf16 v[90:93], v[142:145], v[236:239], v[90:93]
	v_mfma_f32_16x16x32_bf16 v[82:85], v[178:181], v[232:235], v[82:85]
	v_mfma_f32_16x16x32_bf16 v[82:85], v[190:193], v[236:239], v[82:85]
	v_mfma_f32_16x16x32_bf16 v[86:89], v[154:157], v[232:235], v[86:89]
	v_mfma_f32_16x16x32_bf16 v[86:89], v[174:177], v[236:239], v[86:89]
	v_mfma_f32_16x16x32_bf16 v[70:73], v[154:157], v[240:243], v[70:73]
	v_mfma_f32_16x16x32_bf16 v[70:73], v[174:177], v[244:247], v[70:73]
	v_mfma_f32_16x16x32_bf16 v[66:69], v[178:181], v[240:243], v[66:69]
	v_mfma_f32_16x16x32_bf16 v[66:69], v[190:193], v[244:247], v[66:69]
	v_mfma_f32_16x16x32_bf16 v[74:77], v[138:141], v[240:243], v[74:77]
	v_mfma_f32_16x16x32_bf16 v[74:77], v[142:145], v[244:247], v[74:77]
	v_mfma_f32_16x16x32_bf16 v[78:81], v[130:133], v[240:243], v[78:81]
	v_mfma_f32_16x16x32_bf16 v[78:81], v[134:137], v[244:247], v[78:81]
	s_barrier
	s_setprio 0
	s_or_b32 s52, s25, 0x80
	s_mov_b32 m0, s36
	ds_read_b128 v[194:197], v189 offset:49152
	buffer_load_dwordx4 v185, s[44:47], s52 offen lds
	s_add_i32 s25, s25, 0x80080
	s_mov_b32 m0, s37
	ds_read_b128 v[198:201], v189 offset:50176
	buffer_load_dwordx4 v187, s[44:47], s52 offen lds
	s_mov_b32 m0, s66
	ds_read_b128 v[202:205], v189 offset:51200
	buffer_load_dwordx4 v185, s[44:47], s25 offen lds
	s_mov_b32 m0, s67
	ds_read_b128 v[228:231], v189 offset:52224
	buffer_load_dwordx4 v187, s[44:47], s25 offen lds
	s_mov_b32 m0, s48
	ds_read_b128 v[232:235], v189 offset:53248
	buffer_load_dwordx4 v184, s[60:63], s24 offen lds
	s_mov_b32 m0, s49
	ds_read_b128 v[236:239], v189 offset:54272
	buffer_load_dwordx4 v186, s[60:63], s24 offen lds
	ds_read_b128 v[240:243], v189 offset:55296
	ds_read_b128 v[244:247], v189 offset:56320
	s_waitcnt vmcnt(8)
	s_waitcnt lgkmcnt(0)
	s_setprio 1
	s_barrier
	v_mfma_f32_16x16x32_bf16 v[62:65], v[130:133], v[194:197], v[62:65]
	v_mfma_f32_16x16x32_bf16 v[62:65], v[134:137], v[198:201], v[62:65]
	v_mfma_f32_16x16x32_bf16 v[58:61], v[138:141], v[194:197], v[58:61]
	v_mfma_f32_16x16x32_bf16 v[58:61], v[142:145], v[198:201], v[58:61]
	v_mfma_f32_16x16x32_bf16 v[50:53], v[178:181], v[194:197], v[50:53]
	v_mfma_f32_16x16x32_bf16 v[50:53], v[190:193], v[198:201], v[50:53]
	v_mfma_f32_16x16x32_bf16 v[54:57], v[154:157], v[194:197], v[54:57]
	v_mfma_f32_16x16x32_bf16 v[54:57], v[174:177], v[198:201], v[54:57]
	v_mfma_f32_16x16x32_bf16 v[38:41], v[154:157], v[202:205], v[38:41]
	v_mfma_f32_16x16x32_bf16 v[38:41], v[174:177], v[228:231], v[38:41]
	v_mfma_f32_16x16x32_bf16 v[34:37], v[178:181], v[202:205], v[34:37]
	v_mfma_f32_16x16x32_bf16 v[34:37], v[190:193], v[228:231], v[34:37]
	v_mfma_f32_16x16x32_bf16 v[42:45], v[138:141], v[202:205], v[42:45]
	v_mfma_f32_16x16x32_bf16 v[42:45], v[142:145], v[228:231], v[42:45]
	v_mfma_f32_16x16x32_bf16 v[46:49], v[130:133], v[202:205], v[46:49]
	v_mfma_f32_16x16x32_bf16 v[46:49], v[134:137], v[228:231], v[46:49]
	v_mfma_f32_16x16x32_bf16 v[30:33], v[130:133], v[232:235], v[30:33]
	v_mfma_f32_16x16x32_bf16 v[30:33], v[134:137], v[236:239], v[30:33]
	v_mfma_f32_16x16x32_bf16 v[26:29], v[138:141], v[232:235], v[26:29]
	v_mfma_f32_16x16x32_bf16 v[26:29], v[142:145], v[236:239], v[26:29]
	v_mfma_f32_16x16x32_bf16 v[18:21], v[178:181], v[232:235], v[18:21]
	v_mfma_f32_16x16x32_bf16 v[18:21], v[190:193], v[236:239], v[18:21]
	v_mfma_f32_16x16x32_bf16 v[22:25], v[154:157], v[232:235], v[22:25]
	v_mfma_f32_16x16x32_bf16 v[22:25], v[174:177], v[236:239], v[22:25]
	v_mfma_f32_16x16x32_bf16 v[6:9], v[154:157], v[240:243], v[6:9]
	v_mfma_f32_16x16x32_bf16 v[6:9], v[174:177], v[244:247], v[6:9]
	v_mfma_f32_16x16x32_bf16 v[2:5], v[178:181], v[240:243], v[2:5]
	v_mfma_f32_16x16x32_bf16 v[2:5], v[190:193], v[244:247], v[2:5]
	v_mfma_f32_16x16x32_bf16 v[10:13], v[138:141], v[240:243], v[10:13]
	v_mfma_f32_16x16x32_bf16 v[10:13], v[142:145], v[244:247], v[10:13]
	v_mfma_f32_16x16x32_bf16 v[14:17], v[130:133], v[240:243], v[14:17]
	v_mfma_f32_16x16x32_bf16 v[14:17], v[134:137], v[244:247], v[14:17]
	s_barrier
	s_setprio 0
	s_add_i32 s22, s22, 2
	s_addk_i32 s13, 0x100
	s_addk_i32 s21, 0x100
	s_cmp_gt_u32 s22, 29
